# forward substitution: quad transposes of finished blocks issued in the shadow of the following f32 matrix instructions
# baseline (speedup 1.0000x reference)
; #define LAS __attribute__((address_space(3)))
; __device__ __forceinline__ void phase_chunk_prep(const Params& p, LAS unsigned char* lds, int wave_s) {
;     ...
;         if (tid < 256) {
;             const int col = tid; float sol[64];
; #pragma unroll
;             for (int i = 0; i < 64; ++i) sol[i] = 0.f;
; #pragma unroll
;             for (int i = 0; i < 64; ++i) {
;                 float s0 = RHS[i * 256 + col], s1 = 0.f, s2 = 0.f, s3 = 0.f;
; #pragma unroll
;                 for (int j4 = 0; j4 < (i + 3) / 4; ++j4) { const f32x4 a = *(const LAS f32x4*)(AM + i * 64 + 4 * j4);
;                     s0 -= a.x * sol[4 * j4]; s1 -= a.y * sol[4 * j4 + 1]; s2 -= a.z * sol[4 * j4 + 2]; s3 -= a.w * sol[4 * j4 + 3]; }
;                 sol[i] = (s0 + s1) + (s2 + s3);
;             }
.Lfm_not0:
	s_waitcnt lgkmcnt(0)
	s_barrier
	ds_read_b128 v[132:135], v86
	ds_read_b128 v[136:139], v86 offset:1280
	ds_read_b128 v[140:143], v86 offset:2560
	ds_read_b128 v[144:147], v86 offset:3840
	v_xor_b32_e32 v148, 0x80000000, v148
	v_xor_b32_e32 v149, 0x80000000, v149
	v_xor_b32_e32 v150, 0x80000000, v150
	v_xor_b32_e32 v151, 0x80000000, v151
	v_xor_b32_e32 v152, 0x80000000, v152
	v_xor_b32_e32 v153, 0x80000000, v153
	v_xor_b32_e32 v154, 0x80000000, v154
	v_xor_b32_e32 v155, 0x80000000, v155
	v_xor_b32_e32 v156, 0x80000000, v156
	v_xor_b32_e32 v157, 0x80000000, v157
	v_xor_b32_e32 v158, 0x80000000, v158
	v_xor_b32_e32 v159, 0x80000000, v159
	v_xor_b32_e32 v160, 0x80000000, v160
	v_xor_b32_e32 v161, 0x80000000, v161
	v_xor_b32_e32 v162, 0x80000000, v162
	v_xor_b32_e32 v163, 0x80000000, v163
	v_xor_b32_e32 v164, 0x80000000, v164
	v_xor_b32_e32 v165, 0x80000000, v165
	v_xor_b32_e32 v166, 0x80000000, v166
	v_xor_b32_e32 v167, 0x80000000, v167
	v_xor_b32_e32 v168, 0x80000000, v168
	v_xor_b32_e32 v169, 0x80000000, v169
	v_xor_b32_e32 v170, 0x80000000, v170
	v_xor_b32_e32 v171, 0x80000000, v171
	s_waitcnt lgkmcnt(0)
	s_mov_b32 s86, 0xaaaaaaaa
	s_mov_b32 s87, 0xaaaaaaaa
	s_mov_b32 s88, 0xcccccccc
	s_mov_b32 s89, 0xcccccccc
	v_mfma_f32_16x16x4_f32 v[36:39], v132, v0, 0
	v_mfma_f32_16x16x4_f32 v[36:39], v133, v1, v[36:39]
	v_mfma_f32_16x16x4_f32 v[36:39], v134, v2, v[36:39]
	v_mfma_f32_16x16x4_f32 v[36:39], v135, v3, v[36:39]
	v_mfma_f32_16x16x4_f32 v[68:71], v132, v16, 0
	v_mfma_f32_16x16x4_f32 v[68:71], v133, v17, v[68:71]
	v_mfma_f32_16x16x4_f32 v[68:71], v134, v18, v[68:71]
	v_mfma_f32_16x16x4_f32 v[68:71], v135, v19, v[68:71]
	v_mfma_f32_16x16x4_f32 v[4:7], v148, v36, v[4:7]
	v_mfma_f32_16x16x4_f32 v[4:7], v149, v37, v[4:7]
	v_mfma_f32_16x16x4_f32 v[4:7], v150, v38, v[4:7]
	v_mfma_f32_16x16x4_f32 v[4:7], v151, v39, v[4:7]
	v_mfma_f32_16x16x4_f32 v[8:11], v152, v36, v[8:11]
	v_mfma_f32_16x16x4_f32 v[8:11], v153, v37, v[8:11]
	v_mfma_f32_16x16x4_f32 v[8:11], v154, v38, v[8:11]
	v_mfma_f32_16x16x4_f32 v[8:11], v155, v39, v[8:11]
	v_mfma_f32_16x16x4_f32 v[12:15], v160, v36, v[12:15]
	v_mfma_f32_16x16x4_f32 v[12:15], v161, v37, v[12:15]
	v_mfma_f32_16x16x4_f32 v[12:15], v162, v38, v[12:15]
	v_mfma_f32_16x16x4_f32 v[12:15], v163, v39, v[12:15]
	v_mfma_f32_16x16x4_f32 v[20:23], v148, v68, v[20:23]
	v_mfma_f32_16x16x4_f32 v[20:23], v149, v69, v[20:23]
	v_mfma_f32_16x16x4_f32 v[20:23], v150, v70, v[20:23]
	v_mfma_f32_16x16x4_f32 v[20:23], v151, v71, v[20:23]
	v_mfma_f32_16x16x4_f32 v[24:27], v152, v68, v[24:27]
	v_mfma_f32_16x16x4_f32 v[24:27], v153, v69, v[24:27]
	v_mfma_f32_16x16x4_f32 v[24:27], v154, v70, v[24:27]
	v_mfma_f32_16x16x4_f32 v[24:27], v155, v71, v[24:27]
	v_mfma_f32_16x16x4_f32 v[28:31], v160, v68, v[28:31]
	v_mfma_f32_16x16x4_f32 v[28:31], v161, v69, v[28:31]
	v_mfma_f32_16x16x4_f32 v[28:31], v162, v70, v[28:31]
	v_mfma_f32_16x16x4_f32 v[28:31], v163, v71, v[28:31]
	v_mfma_f32_16x16x4_f32 v[40:43], v136, v4, 0
	v_mfma_f32_16x16x4_f32 v[40:43], v137, v5, v[40:43]
	v_mfma_f32_16x16x4_f32 v[40:43], v138, v6, v[40:43]
	v_mfma_f32_16x16x4_f32 v[40:43], v139, v7, v[40:43]
	v_mfma_f32_16x16x4_f32 v[72:75], v136, v20, 0
	v_mfma_f32_16x16x4_f32 v[72:75], v137, v21, v[72:75]
	v_mfma_f32_16x16x4_f32 v[72:75], v138, v22, v[72:75]
	v_mfma_f32_16x16x4_f32 v[72:75], v139, v23, v[72:75]
	s_cmp_gt_u32 s84, 3
	s_cbranch_scc0 .Lfm_nx0
	v_cndmask_b32_e64 v100, v37, v36, s[86:87]
	v_cndmask_b32_e64 v101, v69, v68, s[86:87]
	v_cndmask_b32_e64 v102, v39, v38, s[86:87]
	v_cndmask_b32_e64 v103, v71, v70, s[86:87]
	v_mov_b32_dpp v108, v100 quad_perm:[1,0,3,2] row_mask:0xf bank_mask:0xf
	v_mov_b32_dpp v109, v101 quad_perm:[1,0,3,2] row_mask:0xf bank_mask:0xf
	v_mov_b32_dpp v110, v102 quad_perm:[1,0,3,2] row_mask:0xf bank_mask:0xf
	v_mov_b32_dpp v111, v103 quad_perm:[1,0,3,2] row_mask:0xf bank_mask:0xf
	v_cndmask_b32_e64 v36, v36, v108, s[86:87]
	v_cndmask_b32_e64 v37, v108, v37, s[86:87]
	v_cndmask_b32_e64 v68, v68, v109, s[86:87]
	v_cndmask_b32_e64 v69, v109, v69, s[86:87]
	v_cndmask_b32_e64 v38, v38, v110, s[86:87]
	v_cndmask_b32_e64 v39, v110, v39, s[86:87]
	v_cndmask_b32_e64 v70, v70, v111, s[86:87]
	v_cndmask_b32_e64 v71, v111, v71, s[86:87]
	v_cndmask_b32_e64 v100, v38, v36, s[88:89]
	v_cndmask_b32_e64 v101, v70, v68, s[88:89]
	v_cndmask_b32_e64 v102, v39, v37, s[88:89]
	v_cndmask_b32_e64 v103, v71, v69, s[88:89]
	v_mov_b32_dpp v108, v100 quad_perm:[2,3,0,1] row_mask:0xf bank_mask:0xf
	v_mov_b32_dpp v109, v101 quad_perm:[2,3,0,1] row_mask:0xf bank_mask:0xf
	v_mov_b32_dpp v110, v102 quad_perm:[2,3,0,1] row_mask:0xf bank_mask:0xf
	v_mov_b32_dpp v111, v103 quad_perm:[2,3,0,1] row_mask:0xf bank_mask:0xf
	v_cndmask_b32_e64 v36, v36, v108, s[88:89]
	v_cndmask_b32_e64 v38, v108, v38, s[88:89]
	v_cndmask_b32_e64 v68, v68, v109, s[88:89]
	v_cndmask_b32_e64 v70, v109, v70, s[88:89]
	v_cndmask_b32_e64 v37, v37, v110, s[88:89]
	v_cndmask_b32_e64 v39, v110, v39, s[88:89]
	v_cndmask_b32_e64 v69, v69, v111, s[88:89]
	v_cndmask_b32_e64 v71, v111, v71, s[88:89]
; #define LAS __attribute__((address_space(3)))
; __device__ __forceinline__ void phase_chunk_prep(const Params& p, LAS unsigned char* lds, int wave_s) {
;     ...
;         if (tid < 256) {
;             const int col = tid; float sol[64];
; #pragma unroll
;             for (int i = 0; i < 64; ++i) sol[i] = 0.f;
; #pragma unroll
;             for (int i = 0; i < 64; ++i) {
;                 float s0 = RHS[i * 256 + col], s1 = 0.f, s2 = 0.f, s3 = 0.f;
; #pragma unroll
;                 for (int j4 = 0; j4 < (i + 3) / 4; ++j4) { const f32x4 a = *(const LAS f32x4*)(AM + i * 64 + 4 * j4);
;                     s0 -= a.x * sol[4 * j4]; s1 -= a.y * sol[4 * j4 + 1]; s2 -= a.z * sol[4 * j4 + 2]; s3 -= a.w * sol[4 * j4 + 3]; }
;                 sol[i] = (s0 + s1) + (s2 + s3);
;             }
.Lfm_nx0:
	v_mfma_f32_16x16x4_f32 v[8:11], v156, v40, v[8:11]
	v_mfma_f32_16x16x4_f32 v[8:11], v157, v41, v[8:11]
	v_mfma_f32_16x16x4_f32 v[8:11], v158, v42, v[8:11]
	v_mfma_f32_16x16x4_f32 v[8:11], v159, v43, v[8:11]
	v_mfma_f32_16x16x4_f32 v[12:15], v164, v40, v[12:15]
	v_mfma_f32_16x16x4_f32 v[12:15], v165, v41, v[12:15]
	v_mfma_f32_16x16x4_f32 v[12:15], v166, v42, v[12:15]
	v_mfma_f32_16x16x4_f32 v[12:15], v167, v43, v[12:15]
	v_mfma_f32_16x16x4_f32 v[24:27], v156, v72, v[24:27]
	v_mfma_f32_16x16x4_f32 v[24:27], v157, v73, v[24:27]
	v_mfma_f32_16x16x4_f32 v[24:27], v158, v74, v[24:27]
	v_mfma_f32_16x16x4_f32 v[24:27], v159, v75, v[24:27]
	v_mfma_f32_16x16x4_f32 v[28:31], v164, v72, v[28:31]
	v_mfma_f32_16x16x4_f32 v[28:31], v165, v73, v[28:31]
	v_mfma_f32_16x16x4_f32 v[28:31], v166, v74, v[28:31]
	v_mfma_f32_16x16x4_f32 v[28:31], v167, v75, v[28:31]
	v_mfma_f32_16x16x4_f32 v[44:47], v140, v8, 0
	v_mfma_f32_16x16x4_f32 v[44:47], v141, v9, v[44:47]
	v_mfma_f32_16x16x4_f32 v[44:47], v142, v10, v[44:47]
	v_mfma_f32_16x16x4_f32 v[44:47], v143, v11, v[44:47]
	v_mfma_f32_16x16x4_f32 v[76:79], v140, v24, 0
	v_mfma_f32_16x16x4_f32 v[76:79], v141, v25, v[76:79]
	v_mfma_f32_16x16x4_f32 v[76:79], v142, v26, v[76:79]
	v_mfma_f32_16x16x4_f32 v[76:79], v143, v27, v[76:79]
	s_cmp_gt_u32 s84, 3
	s_cbranch_scc0 .Lfm_nx1
	v_cndmask_b32_e64 v100, v41, v40, s[86:87]
	v_cndmask_b32_e64 v101, v73, v72, s[86:87]
	v_cndmask_b32_e64 v102, v43, v42, s[86:87]
	v_cndmask_b32_e64 v103, v75, v74, s[86:87]
	v_mov_b32_dpp v108, v100 quad_perm:[1,0,3,2] row_mask:0xf bank_mask:0xf
	v_mov_b32_dpp v109, v101 quad_perm:[1,0,3,2] row_mask:0xf bank_mask:0xf
	v_mov_b32_dpp v110, v102 quad_perm:[1,0,3,2] row_mask:0xf bank_mask:0xf
	v_mov_b32_dpp v111, v103 quad_perm:[1,0,3,2] row_mask:0xf bank_mask:0xf
	v_cndmask_b32_e64 v40, v40, v108, s[86:87]
	v_cndmask_b32_e64 v41, v108, v41, s[86:87]
	v_cndmask_b32_e64 v72, v72, v109, s[86:87]
	v_cndmask_b32_e64 v73, v109, v73, s[86:87]
	v_cndmask_b32_e64 v42, v42, v110, s[86:87]
	v_cndmask_b32_e64 v43, v110, v43, s[86:87]
	v_cndmask_b32_e64 v74, v74, v111, s[86:87]
	v_cndmask_b32_e64 v75, v111, v75, s[86:87]
	v_cndmask_b32_e64 v100, v42, v40, s[88:89]
	v_cndmask_b32_e64 v101, v74, v72, s[88:89]
	v_cndmask_b32_e64 v102, v43, v41, s[88:89]
	v_cndmask_b32_e64 v103, v75, v73, s[88:89]
	v_mov_b32_dpp v108, v100 quad_perm:[2,3,0,1] row_mask:0xf bank_mask:0xf
	v_mov_b32_dpp v109, v101 quad_perm:[2,3,0,1] row_mask:0xf bank_mask:0xf
	v_mov_b32_dpp v110, v102 quad_perm:[2,3,0,1] row_mask:0xf bank_mask:0xf
	v_mov_b32_dpp v111, v103 quad_perm:[2,3,0,1] row_mask:0xf bank_mask:0xf
	v_cndmask_b32_e64 v40, v40, v108, s[88:89]
	v_cndmask_b32_e64 v42, v108, v42, s[88:89]
	v_cndmask_b32_e64 v72, v72, v109, s[88:89]
	v_cndmask_b32_e64 v74, v109, v74, s[88:89]
	v_cndmask_b32_e64 v41, v41, v110, s[88:89]
	v_cndmask_b32_e64 v43, v110, v43, s[88:89]
	v_cndmask_b32_e64 v73, v73, v111, s[88:89]
	v_cndmask_b32_e64 v75, v111, v75, s[88:89]
.Lfm_nx1:
	v_mfma_f32_16x16x4_f32 v[12:15], v168, v44, v[12:15]
	v_mfma_f32_16x16x4_f32 v[12:15], v169, v45, v[12:15]
	v_mfma_f32_16x16x4_f32 v[12:15], v170, v46, v[12:15]
	v_mfma_f32_16x16x4_f32 v[12:15], v171, v47, v[12:15]
	v_mfma_f32_16x16x4_f32 v[28:31], v168, v76, v[28:31]
	v_mfma_f32_16x16x4_f32 v[28:31], v169, v77, v[28:31]
	v_mfma_f32_16x16x4_f32 v[28:31], v170, v78, v[28:31]
	v_mfma_f32_16x16x4_f32 v[28:31], v171, v79, v[28:31]
	v_mfma_f32_16x16x4_f32 v[48:51], v144, v12, 0
	v_mfma_f32_16x16x4_f32 v[48:51], v145, v13, v[48:51]
	v_mfma_f32_16x16x4_f32 v[48:51], v146, v14, v[48:51]
	v_mfma_f32_16x16x4_f32 v[48:51], v147, v15, v[48:51]
	v_mfma_f32_16x16x4_f32 v[80:83], v144, v28, 0
	v_mfma_f32_16x16x4_f32 v[80:83], v145, v29, v[80:83]
	v_mfma_f32_16x16x4_f32 v[80:83], v146, v30, v[80:83]
	v_mfma_f32_16x16x4_f32 v[80:83], v147, v31, v[80:83]
	s_cmp_gt_u32 s84, 3
	s_cbranch_scc0 .Lfm_nx2
	v_cndmask_b32_e64 v100, v45, v44, s[86:87]
	v_cndmask_b32_e64 v101, v77, v76, s[86:87]
	v_cndmask_b32_e64 v102, v47, v46, s[86:87]
	v_cndmask_b32_e64 v103, v79, v78, s[86:87]
	v_mov_b32_dpp v108, v100 quad_perm:[1,0,3,2] row_mask:0xf bank_mask:0xf
	v_mov_b32_dpp v109, v101 quad_perm:[1,0,3,2] row_mask:0xf bank_mask:0xf
	v_mov_b32_dpp v110, v102 quad_perm:[1,0,3,2] row_mask:0xf bank_mask:0xf
	v_mov_b32_dpp v111, v103 quad_perm:[1,0,3,2] row_mask:0xf bank_mask:0xf
	v_cndmask_b32_e64 v44, v44, v108, s[86:87]
	v_cndmask_b32_e64 v45, v108, v45, s[86:87]
	v_cndmask_b32_e64 v76, v76, v109, s[86:87]
	v_cndmask_b32_e64 v77, v109, v77, s[86:87]
	v_cndmask_b32_e64 v46, v46, v110, s[86:87]
	v_cndmask_b32_e64 v47, v110, v47, s[86:87]
	v_cndmask_b32_e64 v78, v78, v111, s[86:87]
	v_cndmask_b32_e64 v79, v111, v79, s[86:87]
	v_cndmask_b32_e64 v100, v46, v44, s[88:89]
	v_cndmask_b32_e64 v101, v78, v76, s[88:89]
	v_cndmask_b32_e64 v102, v47, v45, s[88:89]
	v_cndmask_b32_e64 v103, v79, v77, s[88:89]
	v_mov_b32_dpp v108, v100 quad_perm:[2,3,0,1] row_mask:0xf bank_mask:0xf
	v_mov_b32_dpp v109, v101 quad_perm:[2,3,0,1] row_mask:0xf bank_mask:0xf
	v_mov_b32_dpp v110, v102 quad_perm:[2,3,0,1] row_mask:0xf bank_mask:0xf
	v_mov_b32_dpp v111, v103 quad_perm:[2,3,0,1] row_mask:0xf bank_mask:0xf
	v_cndmask_b32_e64 v44, v44, v108, s[88:89]
	v_cndmask_b32_e64 v46, v108, v46, s[88:89]
	v_cndmask_b32_e64 v76, v76, v109, s[88:89]
	v_cndmask_b32_e64 v78, v109, v78, s[88:89]
	v_cndmask_b32_e64 v45, v45, v110, s[88:89]
	v_cndmask_b32_e64 v47, v110, v47, s[88:89]
	v_cndmask_b32_e64 v77, v77, v111, s[88:89]
	v_cndmask_b32_e64 v79, v111, v79, s[88:89]
; __device__ __forceinline__ bf16_t f2bf(float x) { return (bf16_t)(pk2(x, 0.f) & 0xffffu); }
; __device__ __forceinline__ void phase_chunk_prep(const Params& p, LAS unsigned char* lds, int wave_s) {
;     ...
;             if (col < 128) {
; #pragma unroll
;                 for (int mm = 0; mm < 4; ++mm)
; #pragma unroll
;                     for (int q4 = 0; q4 < 4; ++q4)
;                         *(f32x4*)(U + ((((col >> 4) * 4 + mm) * 64 + q4 * 16 + (col & 15)) << 2)) = (f32x4){sol[16 * mm + 4 * q4], sol[16 * mm + 4 * q4 + 1], sol[16 * mm + 4 * q4 + 2], sol[16 * mm + 4 * q4 + 3]};
;             } else {
; #pragma unroll
;                 for (int i = 0; i < 64; ++i) img[IMG_WD + i * SWD + (col - 128)] = f2bf(sol[i]);
;             }
.Lfm_nx2:
	s_cmp_gt_u32 s84, 3
	s_cbranch_scc1 .Lfm_w
	s_lshl_b32 s96, s16, 15
	s_add_u32 s96, s20, s96
	s_addc_u32 s97, s21, 0
	s_lshl_b32 s85, s84, 13
	v_lshl_add_u32 v89, v34, 8, s85
	v_lshl_add_u32 v89, v33, 4, v89
	v_add_u32_e32 v90, 0x1000, v89
	global_store_dwordx4 v89, v[36:39], s[96:97]
	global_store_dwordx4 v89, v[40:43], s[96:97] offset:1024
	global_store_dwordx4 v89, v[44:47], s[96:97] offset:2048
	global_store_dwordx4 v89, v[48:51], s[96:97] offset:3072
	global_store_dwordx4 v90, v[68:71], s[96:97]
	global_store_dwordx4 v90, v[72:75], s[96:97] offset:1024
	global_store_dwordx4 v90, v[76:79], s[96:97] offset:2048
	s_nop 7
	s_nop 1
	global_store_dwordx4 v90, v[80:83], s[96:97] offset:3072
	s_waitcnt vmcnt(8)
	s_branch .LBB0_663
.Lfm_w:
	s_sub_i32 s85, s84, 4
	s_lshl_b32 s85, s85, 6
	v_and_b32_e32 v92, 3, v32
	v_lshl_add_u32 v91, v34, 2, v92
	v_mul_u32_u24_e32 v91, 0x108, v91
	v_bfe_u32 v92, v32, 2, 2
	v_lshl_add_u32 v91, v92, 3, v91
	v_add_u32_e32 v91, s85, v91
	s_nop 3
	v_cndmask_b32_e64 v100, v49, v48, s[86:87]
	v_cndmask_b32_e64 v101, v81, v80, s[86:87]
	v_cndmask_b32_e64 v102, v51, v50, s[86:87]
	v_cndmask_b32_e64 v103, v83, v82, s[86:87]
	v_mov_b32_dpp v108, v100 quad_perm:[1,0,3,2] row_mask:0xf bank_mask:0xf
	v_mov_b32_dpp v109, v101 quad_perm:[1,0,3,2] row_mask:0xf bank_mask:0xf
	v_mov_b32_dpp v110, v102 quad_perm:[1,0,3,2] row_mask:0xf bank_mask:0xf
	v_mov_b32_dpp v111, v103 quad_perm:[1,0,3,2] row_mask:0xf bank_mask:0xf
	v_cndmask_b32_e64 v48, v48, v108, s[86:87]
	v_cndmask_b32_e64 v49, v108, v49, s[86:87]
	v_cndmask_b32_e64 v80, v80, v109, s[86:87]
	v_cndmask_b32_e64 v81, v109, v81, s[86:87]
	v_cndmask_b32_e64 v50, v50, v110, s[86:87]
	v_cndmask_b32_e64 v51, v110, v51, s[86:87]
	v_cndmask_b32_e64 v82, v82, v111, s[86:87]
	v_cndmask_b32_e64 v83, v111, v83, s[86:87]
	v_cndmask_b32_e64 v100, v50, v48, s[88:89]
	v_cndmask_b32_e64 v101, v82, v80, s[88:89]
	v_cndmask_b32_e64 v102, v51, v49, s[88:89]
	v_cndmask_b32_e64 v103, v83, v81, s[88:89]
	v_mov_b32_dpp v108, v100 quad_perm:[2,3,0,1] row_mask:0xf bank_mask:0xf
	v_mov_b32_dpp v109, v101 quad_perm:[2,3,0,1] row_mask:0xf bank_mask:0xf
	v_mov_b32_dpp v110, v102 quad_perm:[2,3,0,1] row_mask:0xf bank_mask:0xf
	v_mov_b32_dpp v111, v103 quad_perm:[2,3,0,1] row_mask:0xf bank_mask:0xf
	v_cndmask_b32_e64 v48, v48, v108, s[88:89]
	v_cndmask_b32_e64 v50, v108, v50, s[88:89]
	v_cndmask_b32_e64 v80, v80, v109, s[88:89]
	v_cndmask_b32_e64 v82, v109, v82, s[88:89]
	v_cndmask_b32_e64 v49, v49, v110, s[88:89]
	v_cndmask_b32_e64 v51, v110, v51, s[88:89]
	v_cndmask_b32_e64 v81, v81, v111, s[88:89]
	v_cndmask_b32_e64 v83, v111, v83, s[88:89]
	s_mov_b64 s[96:97], s[30:31]
	v_cvt_pk_bf16_f32 v100, v36, v37
	v_cvt_pk_bf16_f32 v101, v38, v39
	global_store_dwordx2 v91, v[100:101], s[96:97]
	v_cvt_pk_bf16_f32 v102, v68, v69
	v_cvt_pk_bf16_f32 v103, v70, v71
	global_store_dwordx2 v91, v[102:103], s[96:97] offset:32
	s_add_u32 s96, s96, 0x1080
	s_addc_u32 s97, s97, 0
	v_cvt_pk_bf16_f32 v100, v40, v41
	v_cvt_pk_bf16_f32 v101, v42, v43
	global_store_dwordx2 v91, v[100:101], s[96:97]
	v_cvt_pk_bf16_f32 v102, v72, v73
	v_cvt_pk_bf16_f32 v103, v74, v75
	global_store_dwordx2 v91, v[102:103], s[96:97] offset:32
	s_add_u32 s96, s96, 0x1080
	s_addc_u32 s97, s97, 0
	v_cvt_pk_bf16_f32 v100, v44, v45
	v_cvt_pk_bf16_f32 v101, v46, v47
	global_store_dwordx2 v91, v[100:101], s[96:97]
	v_cvt_pk_bf16_f32 v102, v76, v77
	v_cvt_pk_bf16_f32 v103, v78, v79
	global_store_dwordx2 v91, v[102:103], s[96:97] offset:32
	s_add_u32 s96, s96, 0x1080
	s_addc_u32 s97, s97, 0
	v_cvt_pk_bf16_f32 v100, v48, v49
	v_cvt_pk_bf16_f32 v101, v50, v51
	global_store_dwordx2 v91, v[100:101], s[96:97]
	v_cvt_pk_bf16_f32 v102, v80, v81
	v_cvt_pk_bf16_f32 v103, v82, v83
	global_store_dwordx2 v91, v[102:103], s[96:97] offset:32
	s_waitcnt vmcnt(8)
	s_branch .LBB0_663
